# prologue share of cache-shift copy moved into attention tasks (third batch per task); prologue copy loop disabled
# speedup vs baseline: 1.0143x; 1.0135x over previous
.LBB0_33:
	s_and_b32 s97, s96, 0xffffffc0
	s_add_i32 s0, s14, s97
	v_add_u32_e32 v44, s0, v46
	s_mov_b32 s0, 0
	s_lshl_b32 s71, s94, 9
	v_cmp_gt_i32_e32 vcc, s0, v44
	s_and_saveexec_b64 s[0:1], vcc
	s_cbranch_execz .LBB0_50
	s_add_i32 s4, s97, s71
	s_add_i32 s4, s4, s14
	v_add_u32_e32 v0, s4, v46
	v_add_u32_e32 v45, 0x600000, v0
	s_lshl_b32 s41, s94, 12
	s_mul_i32 s42, s94, 0xfffff200
	s_mov_b64 s[38:39], 0
	s_mov_b32 s43, 0x7fc000
	v_mov_b32_e32 v46, 0x600000
	s_mov_b32 s54, 0x3fdfff
	v_mov_b32_e32 v47, s49
	v_mov_b32_e32 v48, s51
	v_mov_b32_e32 v49, s48
	v_mov_b32_e32 v50, s50
	s_mov_b32 s55, 0x80402011
	s_mov_b32 s58, 0xfff80400
	s_movk_i32 s59, 0x4000
	v_mov_b32_e32 v51, 0x605e000
	v_mov_b32_e32 v52, 0xa05e000
	v_mov_b32_e32 v29, 0
	s_mov_b32 s74, 0x7fbfff
	s_branch .LBB0_36

.LBB0_344:
	s_or_b32 s14, s0, s73
	s_or_b32 s0, s0, s87
	s_add_i32 s0, s0, s85
	s_lshl_b32 s12, s0, 9
	s_cmpk_gt_i32 s0, 0x1fef
	s_cselect_b64 s[18:19], -1, 0
	s_add_i32 s13, s12, 0xffc02000
	s_and_b64 s[0:1], s[18:19], exec
	s_cselect_b32 s15, s13, s12
	s_mul_hi_i32 s0, s15, 0x80402011
	s_add_i32 s0, s0, s15
	s_lshr_b32 s1, s0, 31
	s_ashr_i32 s0, s0, 18
	s_add_i32 s16, s0, s1
	s_add_i32 s17, s16, 1
	s_and_b64 s[12:13], s[18:19], exec
	v_mbcnt_lo_u32_b32 v172, -1, 0
	v_mbcnt_hi_u32_b32 v172, -1, v172
	s_cselect_b32 s12, s51, s49
	s_cselect_b32 s13, s50, s48
	s_and_b32 s1, s14, s88
	s_lshr_b32 s14, s14, s87
	v_ashrrev_i32_e32 v36, 3, v172
	s_or_b32 s1, s1, s84
	s_lshl_b32 s14, s14, s89
	v_subrev_u32_e32 v37, 64, v36
	s_add_i32 s1, s1, s14
	v_lshlrev_b32_e32 v37, s87, v37
	v_lshlrev_b32_e32 v1, 4, v172
	v_add_u32_e32 v37, s1, v37
	v_and_b32_e32 v41, 0x70, v1
	v_max_i32_e32 v37, 0, v37
	v_lshl_or_b32 v163, v37, 7, v41
	v_subrev_u32_e32 v37, 56, v36
	v_lshlrev_b32_e32 v37, s87, v37
	v_add_u32_e32 v37, s1, v37
	v_max_i32_e32 v37, 0, v37
	v_lshl_or_b32 v165, v37, 7, v41
	v_subrev_u32_e32 v37, 48, v36
	v_lshlrev_b32_e32 v37, s87, v37
	v_add_u32_e32 v37, s1, v37
	v_max_i32_e32 v37, 0, v37
	v_lshl_or_b32 v167, v37, 7, v41
	v_subrev_u32_e32 v37, 40, v36
	v_lshlrev_b32_e32 v37, s87, v37
	v_add_u32_e32 v37, s1, v37
	v_max_i32_e32 v37, 0, v37
	v_lshl_or_b32 v186, v37, 7, v41
	v_subrev_u32_e32 v37, 32, v36
	v_lshlrev_b32_e32 v37, s87, v37
	v_add_u32_e32 v37, s1, v37
	v_max_i32_e32 v37, 0, v37
	v_lshl_or_b32 v144, v37, 7, v41
	v_subrev_u32_e32 v37, 24, v36
	v_lshlrev_b32_e32 v37, s87, v37
	v_add_u32_e32 v37, s1, v37
	v_max_i32_e32 v37, 0, v37
	v_lshl_or_b32 v154, v37, 7, v41
	v_add_lshl_u32 v37, v36, -16, s87
	v_add_u32_e32 v37, s1, v37
	v_max_i32_e32 v37, 0, v37
	v_lshl_or_b32 v156, v37, 7, v41
	v_add_lshl_u32 v37, v36, -8, s87
	v_add_u32_e32 v37, s1, v37
	v_max_i32_e32 v37, 0, v37
	v_lshl_or_b32 v158, v37, 7, v41
	v_lshlrev_b32_e32 v37, s87, v36
	v_add_u32_e32 v37, s1, v37
	v_max_i32_e32 v37, 0, v37
	v_lshl_or_b32 v160, v37, 7, v41
	v_add_lshl_u32 v37, v36, 8, s87
	v_add_u32_e32 v37, s1, v37
	v_max_i32_e32 v37, 0, v37
	v_lshl_or_b32 v162, v37, 7, v41
	v_add_lshl_u32 v37, v36, 16, s87
	v_add_u32_e32 v37, s1, v37
	v_and_b32_e32 v176, 31, v172
	v_max_i32_e32 v37, 0, v37
	v_lshlrev_b32_e32 v0, s87, v176
	v_lshl_or_b32 v164, v37, 7, v41
	v_add_lshl_u32 v37, v36, 24, s87
	s_mul_i32 s0, s17, 0x7fc00
	v_add_u32_e32 v174, s1, v0
	v_add_u32_e32 v37, s1, v37
	v_add_u32_e32 v187, s15, v172
	v_ashrrev_i32_e32 v173, 5, v172
	v_add_u32_e32 v0, s34, v174
	v_max_i32_e32 v37, 0, v37
	v_mov_b32_e32 v188, s17
	v_mov_b32_e32 v189, s16
	v_cmp_gt_i32_e32 vcc, s0, v187
	v_mul_lo_u32 v0, v0, s75
	v_lshlrev_b32_e32 v40, 4, v173
	v_lshl_or_b32 v166, v37, 7, v41
	v_cndmask_b32_e32 v37, v188, v189, vcc
	v_lshlrev_b32_e32 v38, 4, v187
	v_add3_u32 v0, v40, s10, v0
	v_lshl_add_u32 v190, v37, 14, v38
	v_add_u32_e32 v37, 64, v187
	v_add_u32_e32 v0, 0xffffff80, v36
	v_add_u32_e32 v8, 0xffffff90, v36
	v_add_u32_e32 v20, 0xffffffa0, v36
	v_add_u32_e32 v28, 0xffffffb0, v36
	v_cmp_gt_i32_e32 vcc, s0, v37
	v_lshlrev_b32_e32 v0, s87, v0
	v_lshlrev_b32_e32 v8, s87, v8
	v_lshlrev_b32_e32 v20, s87, v20
	v_lshlrev_b32_e32 v28, s87, v28
	v_cndmask_b32_e32 v38, v188, v189, vcc
	v_lshlrev_b32_e32 v37, 4, v37
	v_add_u32_e32 v0, s1, v0
	v_add_u32_e32 v8, s1, v8
	v_add_u32_e32 v20, s1, v20
	v_add_u32_e32 v28, s1, v28
	v_lshl_add_u32 v191, v38, 14, v37
	v_add_u32_e32 v37, 0x80, v187
	v_max_i32_e32 v0, 0, v0
	v_max_i32_e32 v8, 0, v8
	v_max_i32_e32 v20, 0, v20
	v_max_i32_e32 v28, 0, v28
	v_cmp_gt_i32_e32 vcc, s0, v37
	v_lshl_or_b32 v124, v0, 7, v41
	v_add_u32_e32 v0, 0xffffff88, v36
	v_lshl_or_b32 v126, v8, 7, v41
	v_add_u32_e32 v8, 0xffffff98, v36
	v_lshl_or_b32 v155, v20, 7, v41
	v_add_u32_e32 v20, 0xffffffa8, v36
	v_lshl_or_b32 v159, v28, 7, v41
	v_add_u32_e32 v28, 0xffffffb8, v36
	v_cndmask_b32_e32 v38, v188, v189, vcc
	v_lshlrev_b32_e32 v37, 4, v37
	v_lshlrev_b32_e32 v0, s87, v0
	v_lshlrev_b32_e32 v8, s87, v8
	v_lshlrev_b32_e32 v20, s87, v20
	v_lshlrev_b32_e32 v28, s87, v28
	v_lshl_add_u32 v192, v38, 14, v37
	v_add_u32_e32 v37, 0xc0, v187
	s_add_u32 s36, s13, 0x4000
	v_add_u32_e32 v0, s1, v0
	v_add_u32_e32 v8, s1, v8
	v_add_u32_e32 v20, s1, v20
	v_add_u32_e32 v28, s1, v28
	v_cmp_gt_i32_e32 vcc, s0, v37
	s_addc_u32 s37, s12, 0
	v_max_i32_e32 v0, 0, v0
	v_max_i32_e32 v8, 0, v8
	v_max_i32_e32 v20, 0, v20
	v_max_i32_e32 v28, 0, v28
	v_cndmask_b32_e32 v38, v188, v189, vcc
	v_lshlrev_b32_e32 v37, 4, v37
	v_lshl_or_b32 v125, v0, 7, v41
	global_load_dwordx4 v[0:3], v124, s[40:41]
	global_load_dwordx4 v[4:7], v125, s[40:41]
	v_lshl_or_b32 v127, v8, 7, v41
	global_load_dwordx4 v[8:11], v126, s[40:41]
	global_load_dwordx4 v[12:15], v127, s[40:41]
	v_lshl_or_b32 v157, v20, 7, v41
	global_load_dwordx4 v[20:23], v155, s[40:41]
	global_load_dwordx4 v[24:27], v157, s[40:41]
	v_lshl_or_b32 v161, v28, 7, v41
	global_load_dwordx4 v[28:31], v159, s[40:41]
	global_load_dwordx4 v[32:35], v161, s[40:41]
	global_load_dwordx4 v[48:51], v163, s[40:41]
	global_load_dwordx4 v[52:55], v165, s[40:41]
	global_load_dwordx4 v[56:59], v167, s[40:41]
	global_load_dwordx4 v[60:63], v186, s[40:41]
	global_load_dwordx4 v[92:95], v154, s[40:41]
	global_load_dwordx4 v[96:99], v156, s[40:41]
	global_load_dwordx4 v[100:103], v158, s[40:41]
	global_load_dwordx4 v[104:107], v160, s[40:41]
	global_load_dwordx4 v[108:111], v162, s[40:41]
	global_load_dwordx4 v[112:115], v164, s[40:41]
	global_load_dwordx4 v[116:119], v144, s[40:41]
	global_load_dwordx4 v[120:123], v166, s[40:41]
	global_load_dwordx4 v[146:149], v190, s[36:37] nt
	global_load_dwordx4 v[150:153], v191, s[36:37] nt
	v_lshl_add_u32 v193, v38, 14, v37
	global_load_dwordx4 v[178:181], v192, s[36:37] nt
	global_load_dwordx4 v[182:185], v193, s[36:37] nt
	s_lshl_b32 s38, s86, 1
	s_add_i32 s38, s38, s85
	s_cmp_eq_u32 s56, 0
	s_cselect_b32 s39, 1, 0
	s_add_i32 s38, s38, s39
	s_min_u32 s38, s38, 0x1fbf
	s_lshl_b32 s38, s38, 8
	s_add_i32 s38, s38, 0x202000
	s_mul_hi_i32 s39, s38, 0x80402011
	s_add_i32 s39, s39, s38
	s_lshr_b32 s20, s39, 31
	s_ashr_i32 s39, s39, 18
	s_add_i32 s39, s39, s20
	s_add_i32 s20, s39, 1
	s_mul_i32 s21, s20, 0x7fc00
	v_add_u32_e32 v220, s38, v172
	v_mov_b32_e32 v224, s20
	v_mov_b32_e32 v225, s39
	v_add_u32_e32 v221, 64, v220
	v_add_u32_e32 v222, 0x80, v220
	v_add_u32_e32 v223, 0xc0, v220
	s_add_u32 s38, s50, 0x4000
	s_addc_u32 s39, s51, 0
	v_cmp_gt_i32_e32 vcc, s21, v220
	v_lshlrev_b32_e32 v220, 4, v220
	s_nop 0
	v_cndmask_b32_e32 v226, v224, v225, vcc
	v_cmp_gt_i32_e32 vcc, s21, v221
	v_lshl_add_u32 v220, v226, 14, v220
	v_lshlrev_b32_e32 v221, 4, v221
	v_cndmask_b32_e32 v226, v224, v225, vcc
	v_cmp_gt_i32_e32 vcc, s21, v222
	v_lshl_add_u32 v221, v226, 14, v221
	v_lshlrev_b32_e32 v222, 4, v222
	v_cndmask_b32_e32 v226, v224, v225, vcc
	v_cmp_gt_i32_e32 vcc, s21, v223
	v_lshl_add_u32 v222, v226, 14, v222
	v_lshlrev_b32_e32 v223, 4, v223
	v_cndmask_b32_e32 v226, v224, v225, vcc
	s_nop 0
	v_lshl_add_u32 v223, v226, 14, v223
	global_load_dwordx4 v[204:207], v220, s[38:39] nt
	global_load_dwordx4 v[208:211], v221, s[38:39] nt
	global_load_dwordx4 v[212:215], v222, s[38:39] nt
	global_load_dwordx4 v[216:219], v223, s[38:39] nt
	s_and_b64 s[12:13], s[18:19], exec
	s_mov_b32 s12, 0xa05e000
	s_cselect_b32 s12, s12, 0x605e000
	s_add_u32 s18, s66, s12
	v_lshlrev_b32_e32 v177, 2, v173
	s_addc_u32 s19, s67, 0
	v_mul_lo_u32 v43, v36, s76
	v_add_u32_e32 v168, s72, v41
	v_add_u32_e32 v44, 0x480, v43
	v_add_u32_e32 v45, 0x900, v43
	v_add_u32_e32 v46, 0xd80, v43
	v_mul_u32_u24_e32 v42, 0x90, v176
	v_add_u32_e32 v175, v168, v43
	v_add_u32_e32 v128, v168, v44
	v_add_u32_e32 v129, v168, v45
	v_add_u32_e32 v130, v168, v46
	s_waitcnt vmcnt(27)
	ds_write_b128 v175, v[0:3]
	s_waitcnt vmcnt(26)
	ds_write_b128 v128, v[4:7]
	s_waitcnt vmcnt(25)
	ds_write_b128 v129, v[8:11]
	s_waitcnt vmcnt(24)
	ds_write_b128 v130, v[12:15]
	v_add3_u32 v131, s72, v42, v40
	ds_read_b128 v[0:3], v131
	ds_read_b128 v[36:39], v131 offset:32
	s_waitcnt lgkmcnt(1)
	v_mfma_f32_32x32x16_bf16 v[0:15], v[0:3], v[240:243], 0
	v_add_u32_e32 v47, s74, v41
	v_add_u32_e32 v132, v47, v43
	v_add3_u32 v133, s74, v42, v40
	ds_read_b128 v[40:43], v131 offset:96
	v_add_u32_e32 v134, v47, v44
	v_add_u32_e32 v135, v47, v45
	v_add_u32_e32 v136, v47, v46
	s_waitcnt lgkmcnt(1)
	v_mfma_f32_32x32x16_bf16 v[0:15], v[36:39], v[244:247], v[0:15]
	ds_read_b128 v[36:39], v131 offset:64
	s_waitcnt vmcnt(23)
	ds_write_b128 v132, v[20:23]
	s_waitcnt vmcnt(22)
	ds_write_b128 v134, v[24:27]
	s_waitcnt vmcnt(21)
	ds_write_b128 v135, v[28:31]
	s_waitcnt vmcnt(20)
	ds_write_b128 v136, v[32:35]
	ds_read_b128 v[20:23], v133
	s_waitcnt lgkmcnt(5)
	v_mfma_f32_32x32x16_bf16 v[0:15], v[36:39], v[248:251], v[0:15]
	v_mfma_f32_32x32x16_bf16 v[0:15], v[40:43], v[252:255], v[0:15]
	s_waitcnt lgkmcnt(0)
	v_mfma_f32_32x32x16_bf16 v[32:47], v[20:23], v[240:243], 0
	ds_read_b128 v[20:23], v133 offset:32
	s_waitcnt lgkmcnt(0)
	v_mfma_f32_32x32x16_bf16 v[32:47], v[20:23], v[244:247], v[32:47]
	ds_read_b128 v[20:23], v133 offset:64
	s_waitcnt lgkmcnt(0)
	v_mfma_f32_32x32x16_bf16 v[32:47], v[20:23], v[248:251], v[32:47]
	ds_read_b128 v[20:23], v133 offset:96
	s_waitcnt vmcnt(19)
	ds_write_b128 v175, v[48:51]
	s_waitcnt vmcnt(18)
	ds_write_b128 v128, v[52:55]
	s_waitcnt vmcnt(17)
	ds_write_b128 v129, v[56:59]
	s_waitcnt vmcnt(16)
	ds_write_b128 v130, v[60:63]
	s_waitcnt lgkmcnt(4)
	v_mfma_f32_32x32x16_bf16 v[32:47], v[20:23], v[252:255], v[32:47]
	ds_read_b128 v[20:23], v131
	s_waitcnt lgkmcnt(0)
	v_mfma_f32_32x32x16_bf16 v[64:79], v[20:23], v[240:243], 0
	ds_read_b128 v[20:23], v131 offset:32
	s_waitcnt lgkmcnt(0)
	v_mfma_f32_32x32x16_bf16 v[64:79], v[20:23], v[244:247], v[64:79]
	ds_read_b128 v[20:23], v131 offset:64
	s_waitcnt lgkmcnt(0)
	v_mfma_f32_32x32x16_bf16 v[64:79], v[20:23], v[248:251], v[64:79]
	ds_read_b128 v[20:23], v131 offset:96
	s_waitcnt vmcnt(9)
	ds_write_b128 v132, v[116:119]
	ds_write_b128 v134, v[92:95]
	ds_write_b128 v135, v[96:99]
	ds_write_b128 v136, v[100:103]
	s_waitcnt lgkmcnt(4)
	v_mfma_f32_32x32x16_bf16 v[64:79], v[20:23], v[252:255], v[64:79]
	ds_read_b128 v[20:23], v133
	s_waitcnt lgkmcnt(0)
	v_mfma_f32_32x32x16_bf16 v[48:63], v[20:23], v[240:243], 0
	ds_read_b128 v[20:23], v133 offset:32
	s_waitcnt lgkmcnt(0)
	v_mfma_f32_32x32x16_bf16 v[48:63], v[20:23], v[244:247], v[48:63]
	ds_read_b128 v[20:23], v133 offset:64
	s_waitcnt lgkmcnt(0)
	v_mfma_f32_32x32x16_bf16 v[48:63], v[20:23], v[248:251], v[48:63]
	ds_read_b128 v[20:23], v133 offset:96
	ds_write_b128 v175, v[104:107]
	ds_write_b128 v128, v[108:111]
	ds_write_b128 v129, v[112:115]
	s_waitcnt vmcnt(8)
	ds_write_b128 v130, v[120:123]
	ds_read_b128 v[92:95], v131 offset:32
	s_waitcnt lgkmcnt(5)
	v_mfma_f32_32x32x16_bf16 v[48:63], v[20:23], v[252:255], v[48:63]
	ds_read_b128 v[20:23], v131
	s_waitcnt lgkmcnt(0)
	v_mfma_f32_32x32x16_bf16 v[16:31], v[20:23], v[240:243], 0
	v_mfma_f32_32x32x16_bf16 v[16:31], v[92:95], v[244:247], v[16:31]
	ds_read_b128 v[88:91], v131 offset:64
	s_waitcnt lgkmcnt(0)
	v_mfma_f32_32x32x16_bf16 v[16:31], v[88:91], v[248:251], v[16:31]
	ds_read_b128 v[84:87], v131 offset:96
	s_waitcnt lgkmcnt(0)
	v_mfma_f32_32x32x16_bf16 v[16:31], v[84:87], v[252:255], v[16:31]
	global_load_dwordx4 v[140:143], v124, s[42:43]
	global_load_dwordx4 v[136:139], v125, s[42:43]
	global_load_dwordx4 v[132:135], v126, s[42:43]
	global_load_dwordx4 v[128:131], v127, s[42:43]
	global_load_dwordx4 v[112:115], v155, s[42:43]
	global_load_dwordx4 v[116:119], v157, s[42:43]
	global_load_dwordx4 v[120:123], v159, s[42:43]
	s_nop 0
	global_load_dwordx4 v[124:127], v161, s[42:43]
	global_load_dwordx4 v[96:99], v163, s[42:43]
	global_load_dwordx4 v[100:103], v165, s[42:43]
	global_load_dwordx4 v[104:107], v167, s[42:43]
	global_load_dwordx4 v[108:111], v186, s[42:43]
	v_add_u32_e32 v80, 0x100, v187
	v_cmp_gt_i32_e32 vcc, s0, v80
	v_lshlrev_b32_e32 v80, 4, v80
	s_waitcnt vmcnt(19)
	global_store_dwordx4 v190, v[146:149], s[18:19] nt
	s_waitcnt vmcnt(19)
	global_store_dwordx4 v191, v[150:153], s[18:19] nt
	s_waitcnt vmcnt(19)
	global_store_dwordx4 v192, v[178:181], s[18:19] nt
	s_waitcnt vmcnt(19)
	global_store_dwordx4 v193, v[182:185], s[18:19] nt
	s_add_u32 s38, s66, 0xa05e000
	s_addc_u32 s39, s67, 0
	s_waitcnt vmcnt(19)
	global_store_dwordx4 v220, v[204:207], s[38:39] nt
	s_waitcnt vmcnt(19)
	global_store_dwordx4 v221, v[208:211], s[38:39] nt
	s_waitcnt vmcnt(19)
	global_store_dwordx4 v222, v[212:215], s[38:39] nt
	s_waitcnt vmcnt(19)
	global_store_dwordx4 v223, v[216:219], s[38:39] nt
	v_cndmask_b32_e32 v81, v188, v189, vcc
	v_lshl_add_u32 v146, v81, 14, v80
	v_add_u32_e32 v80, 0x140, v187
	v_cmp_gt_i32_e32 vcc, s0, v80
	v_add_u32_e32 v88, 0x180, v187
	v_lshlrev_b32_e32 v80, 4, v80
	v_cndmask_b32_e32 v81, v188, v189, vcc
	v_cmp_gt_i32_e32 vcc, s0, v88
	v_lshlrev_b32_e32 v88, 4, v88
	v_lshl_add_u32 v148, v81, 14, v80
	v_cndmask_b32_e32 v89, v188, v189, vcc
	v_lshl_add_u32 v150, v89, 14, v88
	v_add_u32_e32 v88, 0x1c0, v187
	v_cmp_gt_i32_e32 vcc, s0, v88
	v_lshlrev_b32_e32 v88, 4, v88
	global_load_dwordx4 v[84:87], v146, s[36:37] nt
	global_load_dwordx4 v[80:83], v148, s[36:37] nt
	v_cndmask_b32_e32 v89, v188, v189, vcc
	v_lshl_add_u32 v152, v89, 14, v88
	global_load_dwordx4 v[92:95], v150, s[36:37] nt
	global_load_dwordx4 v[88:91], v152, s[36:37] nt
	s_add_i32 s13, s86, 1
	s_cmp_lg_u32 s56, 0
	s_cselect_b32 s12, s86, s13
	s_cselect_b32 s14, 1, 0
	s_min_i32 s12, s12, 2
	s_lshl_b32 s13, s12, 1
	s_or_b32 s14, s14, s73
	s_lshl_b32 s15, -1, s13
	s_andn2_b32 s15, s14, s15
	s_or_b32 s15, s15, s84
	s_lshr_b32 s14, s14, s13
	s_add_i32 s17, s13, 5
	s_lshl_b32 s14, s14, s17
	s_add_i32 s15, s15, s14
	s_add_i32 s15, s15, s34
	v_lshlrev_b32_e32 v194, s13, v176
	v_add_u32_e32 v194, s15, v194
	v_mul_lo_u32 v194, v194, s75
	v_lshlrev_b32_e32 v195, 4, v173
	v_add3_u32 v194, v195, s10, v194
	global_load_dwordx4 v[240:243], v194, s[28:29]
	global_load_dwordx4 v[244:247], v194, s[28:29] offset:32
	global_load_dwordx4 v[248:251], v194, s[28:29] offset:64
	global_load_dwordx4 v[252:255], v194, s[28:29] offset:96
	s_ashr_i32 s0, s1, s87
	s_sub_i32 s1, 0x80, s0
	v_max_i32_e32 v147, s1, v176
	v_sub_u32_e32 v147, v147, v177
	v_cmp_gt_i32_e32 vcc, 1, v147
	s_sub_i32 s1, 0x7f, s0
	s_ashr_i32 s1, s1, 5
	v_cndmask_b32_e32 v192, v171, v0, vcc
	v_cmp_gt_i32_e32 vcc, 2, v147
	s_cmpk_lt_i32 s0, 0x80
	s_cselect_b32 s0, s1, -1
	v_cndmask_b32_e32 v190, v171, v1, vcc
	v_cmp_gt_i32_e32 vcc, 3, v147
	s_mov_b32 s1, 0xff800000
	v_max3_f32 v0, v192, s1, v190
	v_cndmask_b32_e32 v193, v171, v2, vcc
	v_cmp_gt_i32_e32 vcc, 4, v147
	s_cmp_lt_i32 s0, 1
	s_mov_b64 s[36:37], -1
	v_cndmask_b32_e32 v191, v171, v3, vcc
	v_cmp_gt_i32_e32 vcc, 9, v147
	v_max3_f32 v0, v0, v193, v191
	s_nop 0
	v_cndmask_b32_e32 v189, v171, v4, vcc
	v_cmp_gt_i32_e32 vcc, 10, v147
	s_nop 1
	v_cndmask_b32_e32 v187, v171, v5, vcc
	v_cmp_gt_i32_e32 vcc, 11, v147
	v_max3_f32 v0, v0, v189, v187
	s_nop 0
	v_cndmask_b32_e32 v188, v171, v6, vcc
	v_cmp_gt_i32_e32 vcc, 12, v147
	s_nop 1
	v_cndmask_b32_e32 v186, v171, v7, vcc
	v_cmp_gt_i32_e32 vcc, 17, v147
	v_max3_f32 v0, v0, v188, v186
	s_nop 0
	v_cndmask_b32_e32 v185, v171, v8, vcc
	v_cmp_gt_i32_e32 vcc, 18, v147
	s_nop 1
	v_cndmask_b32_e32 v183, v171, v9, vcc
	v_cmp_gt_i32_e32 vcc, 19, v147
	v_max3_f32 v0, v0, v185, v183
	s_nop 0
	v_cndmask_b32_e32 v184, v171, v10, vcc
	v_cmp_gt_i32_e32 vcc, 20, v147
	s_nop 1
	v_cndmask_b32_e32 v182, v171, v11, vcc
	v_cmp_gt_i32_e32 vcc, 25, v147
	v_max3_f32 v0, v0, v184, v182
	s_nop 0
	v_cndmask_b32_e32 v181, v171, v12, vcc
	v_cmp_gt_i32_e32 vcc, 26, v147
	s_nop 1
	v_cndmask_b32_e32 v179, v171, v13, vcc
	v_cmp_gt_i32_e32 vcc, 27, v147
	v_max3_f32 v0, v0, v181, v179
	s_nop 0
	v_cndmask_b32_e32 v180, v171, v14, vcc
	v_cmp_gt_i32_e32 vcc, 28, v147
	s_nop 1
	v_cndmask_b32_e32 v178, v171, v15, vcc
	v_max3_f32 v149, v0, v180, v178
	s_cbranch_scc1 .LBB0_346
	v_cmp_gt_i32_e32 vcc, 33, v147
	s_nop 1
	v_cndmask_b32_e32 v0, v171, v32, vcc
	v_cmp_gt_i32_e32 vcc, 34, v147
	s_nop 1
	v_cndmask_b32_e32 v1, v171, v33, vcc
	v_cmp_gt_i32_e32 vcc, 35, v147
	v_max3_f32 v4, v149, v0, v1
	s_nop 0
	v_cndmask_b32_e32 v2, v171, v34, vcc
	v_cmp_gt_i32_e32 vcc, 36, v147
	s_nop 1
	v_cndmask_b32_e32 v3, v171, v35, vcc
	v_cmp_gt_i32_e32 vcc, 41, v147
	v_max3_f32 v6, v4, v2, v3
	s_nop 0
	v_cndmask_b32_e32 v4, v171, v36, vcc
	v_cmp_gt_i32_e32 vcc, 42, v147
	s_nop 1
	v_cndmask_b32_e32 v5, v171, v37, vcc
	v_cmp_gt_i32_e32 vcc, 43, v147
	v_max3_f32 v8, v6, v4, v5
	s_nop 0
	v_cndmask_b32_e32 v6, v171, v38, vcc
	v_cmp_gt_i32_e32 vcc, 44, v147
	s_nop 1
	v_cndmask_b32_e32 v7, v171, v39, vcc
	v_cmp_gt_i32_e32 vcc, 49, v147
	v_max3_f32 v10, v8, v6, v7
	s_nop 0
	v_cndmask_b32_e32 v8, v171, v40, vcc
	v_cmp_gt_i32_e32 vcc, 50, v147
	s_nop 1
	v_cndmask_b32_e32 v9, v171, v41, vcc
	v_cmp_gt_i32_e32 vcc, 51, v147
	v_max3_f32 v12, v10, v8, v9
	s_nop 0
	v_cndmask_b32_e32 v10, v171, v42, vcc
	v_cmp_gt_i32_e32 vcc, 52, v147
	s_nop 1
	v_cndmask_b32_e32 v11, v171, v43, vcc
	v_cmp_gt_i32_e32 vcc, 57, v147
	v_max3_f32 v14, v12, v10, v11
	s_nop 0
	v_cndmask_b32_e32 v12, v171, v44, vcc
	v_cmp_gt_i32_e32 vcc, 58, v147
	s_nop 1
	v_cndmask_b32_e32 v13, v171, v45, vcc
	v_cmp_gt_i32_e32 vcc, 59, v147
	v_max3_f32 v151, v14, v12, v13
	s_nop 0
	v_cndmask_b32_e32 v14, v171, v46, vcc
	v_cmp_gt_i32_e32 vcc, 60, v147
	s_nop 1
	v_cndmask_b32_e32 v15, v171, v47, vcc
	v_max3_f32 v151, v151, v14, v15
	s_cbranch_execnz .LBB0_348
	s_branch .LBB0_347

.LBB0_356:
	v_and_b32_e32 v49, 16, v172
	v_lshlrev_b32_e32 v50, 2, v172
	v_and_or_b32 v49, v50, 12, v49
	v_or_b32_e32 v50, 0x80, v176
	v_sub_u32_e32 v50, v50, v177
	s_movk_i32 s0, 0x7f
	v_cmp_lt_i32_e32 vcc, s0, v50
	s_movk_i32 s0, 0x80
	v_lshrrev_b32_e32 v48, 2, v172
	v_cndmask_b32_e32 v16, v171, v16, vcc
	v_cmp_lt_i32_e32 vcc, s0, v50
	s_movk_i32 s0, 0x81
	v_and_or_b32 v48, v48, 3, v177
	v_cndmask_b32_e32 v17, v171, v17, vcc
	v_cmp_lt_i32_e32 vcc, s0, v50
	s_movk_i32 s0, 0x82
	v_mov_b32_e32 v155, v145
	v_cndmask_b32_e32 v18, v171, v18, vcc
	v_cmp_lt_i32_e32 vcc, s0, v50
	s_movk_i32 s0, 0x87
	v_mov_b32_e32 v157, v145
	v_cndmask_b32_e32 v19, v171, v19, vcc
	v_cmp_lt_i32_e32 vcc, s0, v50
	s_movk_i32 s0, 0x88
	v_mov_b32_e32 v159, v145
	v_cndmask_b32_e32 v20, v171, v20, vcc
	v_cmp_lt_i32_e32 vcc, s0, v50
	s_movk_i32 s0, 0x89
	v_mov_b32_e32 v161, v145
	v_cndmask_b32_e32 v21, v171, v21, vcc
	v_cmp_lt_i32_e32 vcc, s0, v50
	s_movk_i32 s0, 0x8a
	v_mov_b32_e32 v163, v145
	v_cndmask_b32_e32 v22, v171, v22, vcc
	v_cmp_lt_i32_e32 vcc, s0, v50
	s_movk_i32 s0, 0x8f
	v_mov_b32_e32 v165, v145
	v_cndmask_b32_e32 v23, v171, v23, vcc
	v_cmp_lt_i32_e32 vcc, s0, v50
	s_movk_i32 s0, 0x91
	v_mov_b32_e32 v167, v145
	v_cndmask_b32_e32 v24, v171, v24, vcc
	v_cmp_lt_i32_e32 vcc, s76, v50
	v_mov_b32_e32 v147, v145
	v_mov_b32_e32 v149, v145
	v_cndmask_b32_e32 v25, v171, v25, vcc
	v_cmp_lt_i32_e32 vcc, s0, v50
	s_movk_i32 s0, 0x92
	v_mov_b32_e32 v151, v145
	v_cndmask_b32_e32 v26, v171, v26, vcc
	v_cmp_lt_i32_e32 vcc, s0, v50
	s_movk_i32 s0, 0x97
	v_mov_b32_e32 v153, v145
	v_cndmask_b32_e32 v27, v171, v27, vcc
	v_cmp_lt_i32_e32 vcc, s0, v50
	s_movk_i32 s0, 0x98
	v_mul_lo_u32 v48, v48, s76
	v_cndmask_b32_e32 v28, v171, v28, vcc
	v_cmp_lt_i32_e32 vcc, s0, v50
	s_movk_i32 s0, 0x99
	v_lshlrev_b32_e32 v49, 1, v49
	v_cndmask_b32_e32 v29, v171, v29, vcc
	v_cmp_lt_i32_e32 vcc, s0, v50
	s_movk_i32 s0, 0x9a
	s_nop 0
	v_cndmask_b32_e32 v30, v171, v30, vcc
	v_cmp_lt_i32_e32 vcc, s0, v50
	v_max3_f32 v50, v70, v16, v17
	v_max3_f32 v50, v50, v18, v19
	v_max3_f32 v50, v50, v20, v21
	v_max3_f32 v50, v50, v22, v23
	v_max3_f32 v50, v50, v24, v25
	v_max3_f32 v50, v50, v26, v27
	v_cndmask_b32_e32 v31, v171, v31, vcc
	v_max3_f32 v50, v50, v28, v29
	v_max3_f32 v50, v50, v30, v31
	v_mov_b32_e32 v51, v50
	s_nop 1
	v_permlane32_swap_b32_e32 v50, v51
	v_max_f32_e32 v51, v51, v51
	v_max_f32_e32 v50, v50, v50
	v_max_f32_e32 v70, v50, v51
	v_mul_f32_e32 v50, 0x3e38aa3b, v70
	v_fma_f32 v51, v192, s77, -v50
	v_exp_f32_e32 v51, v51
	v_fma_f32 v52, v190, s77, -v50
	v_exp_f32_e32 v52, v52
	v_fma_f32 v53, v193, s77, -v50
	v_exp_f32_e32 v53, v53
	v_fma_f32 v54, v191, s77, -v50
	v_exp_f32_e32 v54, v54
	v_fma_f32 v56, v189, s77, -v50
	v_add_f32_e32 v55, 0, v51
	v_exp_f32_e32 v56, v56
	v_fma_f32 v57, v187, s77, -v50
	v_add_f32_e32 v55, v52, v55
	v_exp_f32_e32 v57, v57
	v_fma_f32 v58, v188, s77, -v50
	v_add_f32_e32 v55, v53, v55
	v_exp_f32_e32 v58, v58
	v_fma_f32 v59, v186, s77, -v50
	v_add_f32_e32 v55, v54, v55
	v_exp_f32_e32 v59, v59
	v_fma_f32 v60, v185, s77, -v50
	v_add_f32_e32 v55, v56, v55
	v_exp_f32_e32 v60, v60
	v_fma_f32 v61, v183, s77, -v50
	v_add_f32_e32 v55, v57, v55
	v_exp_f32_e32 v61, v61
	v_fma_f32 v62, v184, s77, -v50
	v_add_f32_e32 v55, v58, v55
	v_exp_f32_e32 v62, v62
	v_fma_f32 v63, v182, s77, -v50
	v_add_f32_e32 v55, v59, v55
	v_exp_f32_e32 v63, v63
	v_fma_f32 v176, v181, s77, -v50
	v_add_f32_e32 v55, v60, v55
	v_exp_f32_e32 v193, v176
	v_fma_f32 v176, v179, s77, -v50
	v_add_f32_e32 v55, v61, v55
	v_exp_f32_e32 v195, v176
	v_fma_f32 v176, v180, s77, -v50
	v_add_f32_e32 v55, v62, v55
	v_exp_f32_e32 v196, v176
	v_fma_f32 v176, v178, s77, -v50
	v_add_f32_e32 v55, v63, v55
	v_exp_f32_e32 v197, v176
	v_fma_f32 v0, v0, s77, -v50
	v_add_f32_e32 v55, v193, v55
	v_exp_f32_e32 v198, v0
	v_fma_f32 v0, v1, s77, -v50
	v_add_f32_e32 v55, v195, v55
	v_exp_f32_e32 v199, v0
	v_fma_f32 v0, v2, s77, -v50
	v_add_f32_e32 v55, v196, v55
	v_exp_f32_e32 v200, v0
	v_fma_f32 v0, v3, s77, -v50
	v_add_f32_e32 v55, v197, v55
	v_exp_f32_e32 v201, v0
	v_fma_f32 v1, v4, s77, -v50
	v_add_f32_e32 v0, v198, v55
	v_exp_f32_e32 v202, v1
	v_fma_f32 v1, v5, s77, -v50
	v_add_f32_e32 v0, v199, v0
	v_exp_f32_e32 v203, v1
	v_fma_f32 v1, v6, s77, -v50
	v_add_f32_e32 v0, v200, v0
	v_exp_f32_e32 v204, v1
	v_fma_f32 v1, v7, s77, -v50
	v_add_f32_e32 v0, v201, v0
	v_exp_f32_e32 v205, v1
	v_fma_f32 v1, v8, s77, -v50
	v_add_f32_e32 v0, v202, v0
	v_exp_f32_e32 v206, v1
	v_fma_f32 v1, v9, s77, -v50
	v_add_f32_e32 v0, v203, v0
	v_exp_f32_e32 v207, v1
	v_fma_f32 v1, v10, s77, -v50
	v_add_f32_e32 v0, v204, v0
	v_exp_f32_e32 v208, v1
	v_fma_f32 v1, v11, s77, -v50
	v_add_f32_e32 v0, v205, v0
	v_exp_f32_e32 v209, v1
	v_fma_f32 v1, v12, s77, -v50
	v_add_f32_e32 v0, v206, v0
	v_exp_f32_e32 v210, v1
	v_fma_f32 v1, v13, s77, -v50
	v_add_f32_e32 v0, v207, v0
	v_exp_f32_e32 v211, v1
	v_fma_f32 v1, v14, s77, -v50
	v_add_f32_e32 v0, v208, v0
	v_exp_f32_e32 v212, v1
	v_fma_f32 v1, v15, s77, -v50
	v_add_f32_e32 v0, v209, v0
	v_exp_f32_e32 v213, v1
	v_fma_f32 v1, v32, s77, -v50
	v_add_f32_e32 v0, v210, v0
	v_exp_f32_e32 v214, v1
	v_fma_f32 v1, v33, s77, -v50
	v_add_f32_e32 v0, v211, v0
	v_exp_f32_e32 v215, v1
	v_fma_f32 v1, v34, s77, -v50
	v_add_f32_e32 v0, v212, v0
	v_exp_f32_e32 v216, v1
	v_fma_f32 v1, v35, s77, -v50
	v_add_f32_e32 v0, v213, v0
	v_exp_f32_e32 v217, v1
	v_fma_f32 v1, v36, s77, -v50
	v_add_f32_e32 v0, v214, v0
	v_exp_f32_e32 v218, v1
	v_fma_f32 v1, v37, s77, -v50
	v_add_f32_e32 v0, v215, v0
	v_exp_f32_e32 v219, v1
	v_fma_f32 v1, v38, s77, -v50
	v_add_f32_e32 v0, v216, v0
	v_exp_f32_e32 v220, v1
	v_fma_f32 v1, v39, s77, -v50
	v_add_f32_e32 v0, v217, v0
	v_exp_f32_e32 v221, v1
	v_fma_f32 v1, v40, s77, -v50
	v_add_f32_e32 v0, v218, v0
	v_exp_f32_e32 v222, v1
	v_fma_f32 v1, v41, s77, -v50
	v_add_f32_e32 v0, v219, v0
	v_exp_f32_e32 v223, v1
	v_fma_f32 v1, v42, s77, -v50
	v_add_f32_e32 v0, v220, v0
	v_exp_f32_e32 v224, v1
	v_fma_f32 v1, v43, s77, -v50
	v_add_f32_e32 v0, v221, v0
	v_exp_f32_e32 v225, v1
	v_fma_f32 v1, v44, s77, -v50
	v_add_f32_e32 v0, v222, v0
	v_exp_f32_e32 v226, v1
	v_fma_f32 v1, v45, s77, -v50
	v_add_f32_e32 v0, v223, v0
	v_exp_f32_e32 v227, v1
	v_fma_f32 v1, v46, s77, -v50
	v_add_f32_e32 v0, v224, v0
	v_exp_f32_e32 v228, v1
	v_fma_f32 v1, v47, s77, -v50
	v_add_f32_e32 v0, v225, v0
	v_exp_f32_e32 v229, v1
	v_fma_f32 v1, v64, s77, -v50
	v_add_f32_e32 v0, v226, v0
	v_exp_f32_e32 v230, v1
	v_fma_f32 v1, v65, s77, -v50
	v_add_f32_e32 v0, v227, v0
	v_exp_f32_e32 v231, v1
	v_fma_f32 v1, v66, s77, -v50
	v_add_f32_e32 v0, v228, v0
	v_exp_f32_e32 v232, v1
	v_fma_f32 v1, v68, s77, -v50
	v_add_f32_e32 v0, v229, v0
	v_exp_f32_e32 v233, v1
	v_fma_f32 v1, v67, s77, -v50
	v_add_f32_e32 v0, v230, v0
	v_exp_f32_e32 v234, v1
	v_fma_f32 v1, v69, s77, -v50
	v_add_f32_e32 v0, v231, v0
	v_exp_f32_e32 v235, v1
	v_fma_f32 v1, v71, s77, -v50
	v_add_f32_e32 v0, v232, v0
	v_exp_f32_e32 v236, v1
	v_fma_f32 v1, v73, s77, -v50
	v_add_f32_e32 v0, v233, v0
	v_exp_f32_e32 v237, v1
	v_fma_f32 v1, v72, s77, -v50
	v_add_f32_e32 v0, v234, v0
	v_exp_f32_e32 v186, v1
	v_fma_f32 v1, v74, s77, -v50
	v_add_f32_e32 v0, v235, v0
	v_exp_f32_e32 v187, v1
	v_fma_f32 v1, v75, s77, -v50
	v_add_f32_e32 v0, v236, v0
	v_exp_f32_e32 v188, v1
	v_fma_f32 v1, v77, s77, -v50
	v_add_f32_e32 v0, v237, v0
	v_exp_f32_e32 v189, v1
	v_fma_f32 v1, v76, s77, -v50
	v_add_f32_e32 v0, v186, v0
	v_exp_f32_e32 v190, v1
	v_fma_f32 v1, v78, s77, -v50
	v_add_f32_e32 v0, v187, v0
	v_exp_f32_e32 v191, v1
	v_fma_f32 v1, v79, s77, -v50
	v_add_f32_e32 v0, v188, v0
	v_exp_f32_e32 v192, v1
	v_fma_f32 v1, v194, s77, -v50
	v_add_f32_e32 v0, v189, v0
	v_exp_f32_e32 v194, v1
	v_fma_f32 v1, v16, s77, -v50
	v_add_f32_e32 v0, v190, v0
	v_exp_f32_e32 v178, v1
	v_fma_f32 v1, v17, s77, -v50
	v_add_f32_e32 v0, v191, v0
	v_exp_f32_e32 v179, v1
	v_fma_f32 v1, v18, s77, -v50
	v_add_f32_e32 v0, v192, v0
	v_exp_f32_e32 v180, v1
	v_fma_f32 v1, v19, s77, -v50
	v_add_f32_e32 v0, v194, v0
	v_exp_f32_e32 v181, v1
	v_fma_f32 v1, v20, s77, -v50
	v_add_f32_e32 v0, v178, v0
	v_exp_f32_e32 v182, v1
	v_fma_f32 v1, v21, s77, -v50
	v_add_f32_e32 v0, v179, v0
	v_exp_f32_e32 v183, v1
	v_fma_f32 v1, v22, s77, -v50
	v_add_f32_e32 v0, v180, v0
	v_exp_f32_e32 v184, v1
	v_fma_f32 v1, v23, s77, -v50
	v_add_f32_e32 v0, v181, v0
	v_exp_f32_e32 v185, v1
	v_fma_f32 v1, v24, s77, -v50
	v_add_f32_e32 v0, v182, v0
	v_exp_f32_e32 v73, v1
	v_fma_f32 v1, v25, s77, -v50
	v_add_f32_e32 v0, v183, v0
	v_exp_f32_e32 v74, v1
	v_fma_f32 v1, v26, s77, -v50
	v_add_f32_e32 v0, v184, v0
	v_exp_f32_e32 v75, v1
	v_fma_f32 v1, v27, s77, -v50
	v_add_f32_e32 v0, v185, v0
	v_exp_f32_e32 v77, v1
	v_fma_f32 v1, v28, s77, -v50
	v_add_f32_e32 v0, v73, v0
	v_exp_f32_e32 v78, v1
	v_fma_f32 v1, v29, s77, -v50
	v_add_f32_e32 v0, v74, v0
	v_exp_f32_e32 v79, v1
	v_fma_f32 v1, v30, s77, -v50
	v_add_f32_e32 v0, v75, v0
	v_exp_f32_e32 v176, v1
	v_fma_f32 v1, v31, s77, -v50
	v_add_f32_e32 v0, v77, v0
	v_exp_f32_e32 v177, v1
	v_add_f32_e32 v0, v78, v0
	v_add_f32_e32 v0, v79, v0
	v_add_f32_e32 v0, v176, v0
	v_add_f32_e32 v71, v177, v0
	v_mov_b32_e32 v72, v71
	s_nop 1
	v_permlane32_swap_b32_e32 v71, v72
	v_add_u32_e32 v0, 64, v172
	v_lshrrev_b32_e32 v0, 3, v0
	v_mad_u64_u32 v[64:65], s[0:1], v0, s76, v[168:169]
	v_add_u32_e32 v0, 0x80, v172
	v_lshrrev_b32_e32 v0, 3, v0
	v_mad_u64_u32 v[66:67], s[0:1], v0, s76, v[168:169]
	v_add_u32_e32 v0, 0xc0, v172
	v_lshrrev_b32_e32 v0, 3, v0
	v_mad_u64_u32 v[68:69], s[0:1], v0, s76, v[168:169]
	v_add3_u32 v76, s72, v48, v49
	s_waitcnt vmcnt(27)
	ds_write_b128 v175, v[140:143]
	s_waitcnt vmcnt(26)
	ds_write_b128 v64, v[136:139]
	s_waitcnt vmcnt(25)
	ds_write_b128 v66, v[132:135]
	s_waitcnt vmcnt(24)
	ds_write_b128 v68, v[128:131]
	ds_read_b64_tr_b16 v[0:1], v76
	ds_read_b64_tr_b16 v[2:3], v76 offset:1152
	ds_read_b64_tr_b16 v[10:11], v76 offset:1216
	ds_read_b64_tr_b16 v[8:9], v76 offset:64
	v_cvt_pk_bf16_f32 v4, v51, v52
	v_cvt_pk_bf16_f32 v5, v53, v54
	v_cvt_pk_bf16_f32 v6, v56, v57
	v_cvt_pk_bf16_f32 v7, v58, v59
	ds_read_b64_tr_b16 v[32:33], v76 offset:2304
	ds_read_b64_tr_b16 v[34:35], v76 offset:3456
	s_waitcnt lgkmcnt(4)
	v_mfma_f32_32x32x16_bf16 v[16:31], v[0:3], v[4:7], 0
	ds_read_b64_tr_b16 v[42:43], v76 offset:3520
	ds_read_b64_tr_b16 v[40:41], v76 offset:2368
	v_cvt_pk_bf16_f32 v36, v60, v61
	v_cvt_pk_bf16_f32 v37, v62, v63
	v_cvt_pk_bf16_f32 v38, v193, v195
	v_cvt_pk_bf16_f32 v39, v196, v197
	s_waitcnt lgkmcnt(4)
	v_mfma_f32_32x32x16_bf16 v[0:15], v[8:11], v[4:7], 0
	s_waitcnt lgkmcnt(2)
	v_mfma_f32_32x32x16_bf16 v[16:31], v[32:35], v[36:39], v[16:31]
	s_waitcnt lgkmcnt(0)
	v_mfma_f32_32x32x16_bf16 v[0:15], v[40:43], v[36:39], v[0:15]
	v_lshl_add_u64 v[32:33], s[42:43], 0, v[144:145]
	v_lshl_add_u64 v[34:35], s[42:43], 0, v[154:155]
	global_load_dwordx4 v[48:51], v[32:33], off
	global_load_dwordx4 v[52:55], v[34:35], off
	v_lshl_add_u64 v[32:33], s[42:43], 0, v[156:157]
	v_lshl_add_u64 v[34:35], s[42:43], 0, v[158:159]
	global_load_dwordx4 v[56:59], v[32:33], off
	global_load_dwordx4 v[60:63], v[34:35], off
	v_lshl_add_u64 v[32:33], s[42:43], 0, v[160:161]
	v_lshl_add_u64 v[36:37], s[42:43], 0, v[162:163]
	v_lshl_add_u64 v[40:41], s[42:43], 0, v[164:165]
	v_lshl_add_u64 v[44:45], s[42:43], 0, v[166:167]
	global_load_dwordx4 v[32:35], v[32:33], off
	s_nop 0
	global_load_dwordx4 v[36:39], v[36:37], off
	s_nop 0
	global_load_dwordx4 v[40:43], v[40:41], off
	s_nop 0
	global_load_dwordx4 v[44:47], v[44:45], off
	s_waitcnt vmcnt(31)
	ds_write_b128 v175, v[112:115]
	s_waitcnt vmcnt(30)
	ds_write_b128 v64, v[116:119]
	s_waitcnt vmcnt(29)
	ds_write_b128 v66, v[120:123]
	s_waitcnt vmcnt(28)
	ds_write_b128 v68, v[124:127]
	ds_read_b64_tr_b16 v[116:117], v76
	ds_read_b64_tr_b16 v[118:119], v76 offset:1152
	ds_read_b64_tr_b16 v[120:121], v76 offset:64
	ds_read_b64_tr_b16 v[122:123], v76 offset:1216
	v_cvt_pk_bf16_f32 v112, v198, v199
	v_cvt_pk_bf16_f32 v113, v200, v201
	v_cvt_pk_bf16_f32 v114, v202, v203
	v_cvt_pk_bf16_f32 v115, v204, v205
	s_waitcnt lgkmcnt(2)
	s_nop 0
	v_mfma_f32_32x32x16_bf16 v[16:31], v[116:119], v[112:115], v[16:31]
	s_waitcnt lgkmcnt(0)
	v_mfma_f32_32x32x16_bf16 v[0:15], v[120:123], v[112:115], v[0:15]
	ds_read_b64_tr_b16 v[116:117], v76 offset:2304
	ds_read_b64_tr_b16 v[118:119], v76 offset:3456
	ds_read_b64_tr_b16 v[120:121], v76 offset:2368
	ds_read_b64_tr_b16 v[122:123], v76 offset:3520
	v_cvt_pk_bf16_f32 v112, v206, v207
	v_cvt_pk_bf16_f32 v113, v208, v209
	v_cvt_pk_bf16_f32 v114, v210, v211
	v_cvt_pk_bf16_f32 v115, v212, v213
	s_waitcnt lgkmcnt(2)
	s_nop 0
	v_mfma_f32_32x32x16_bf16 v[16:31], v[116:119], v[112:115], v[16:31]
	s_waitcnt lgkmcnt(0)
	v_mfma_f32_32x32x16_bf16 v[0:15], v[120:123], v[112:115], v[0:15]
	s_waitcnt vmcnt(27)
	ds_write_b128 v175, v[96:99]
	s_waitcnt vmcnt(26)
	ds_write_b128 v64, v[100:103]
	s_waitcnt vmcnt(25)
	ds_write_b128 v66, v[104:107]
	s_waitcnt vmcnt(24)
	ds_write_b128 v68, v[108:111]
	ds_read_b64_tr_b16 v[100:101], v76
	ds_read_b64_tr_b16 v[102:103], v76 offset:1152
	ds_read_b64_tr_b16 v[104:105], v76 offset:64
	ds_read_b64_tr_b16 v[106:107], v76 offset:1216
	v_cvt_pk_bf16_f32 v96, v214, v215
	v_cvt_pk_bf16_f32 v97, v216, v217
	v_cvt_pk_bf16_f32 v98, v218, v219
	v_cvt_pk_bf16_f32 v99, v220, v221
	s_waitcnt lgkmcnt(2)
	s_nop 0
	v_mfma_f32_32x32x16_bf16 v[16:31], v[100:103], v[96:99], v[16:31]
	s_waitcnt lgkmcnt(0)
	v_mfma_f32_32x32x16_bf16 v[0:15], v[104:107], v[96:99], v[0:15]
	ds_read_b64_tr_b16 v[100:101], v76 offset:2304
	ds_read_b64_tr_b16 v[102:103], v76 offset:3456
	ds_read_b64_tr_b16 v[104:105], v76 offset:2368
	ds_read_b64_tr_b16 v[106:107], v76 offset:3520
	v_cvt_pk_bf16_f32 v96, v222, v223
	v_cvt_pk_bf16_f32 v97, v224, v225
	v_cvt_pk_bf16_f32 v98, v226, v227
	v_cvt_pk_bf16_f32 v99, v228, v229
	s_waitcnt lgkmcnt(2)
	s_nop 0
	v_mfma_f32_32x32x16_bf16 v[16:31], v[100:103], v[96:99], v[16:31]
	s_waitcnt lgkmcnt(0)
	v_mfma_f32_32x32x16_bf16 v[0:15], v[104:107], v[96:99], v[0:15]
	s_waitcnt vmcnt(7)
	ds_write_b128 v175, v[48:51]
	s_waitcnt vmcnt(6)
	ds_write_b128 v64, v[52:55]
	s_waitcnt vmcnt(5)
	ds_write_b128 v66, v[56:59]
	s_waitcnt vmcnt(4)
	ds_write_b128 v68, v[60:63]
	ds_read_b64_tr_b16 v[52:53], v76
	ds_read_b64_tr_b16 v[54:55], v76 offset:1152
	ds_read_b64_tr_b16 v[56:57], v76 offset:64
	ds_read_b64_tr_b16 v[58:59], v76 offset:1216
	v_cvt_pk_bf16_f32 v48, v230, v231
	v_cvt_pk_bf16_f32 v49, v232, v233
	v_cvt_pk_bf16_f32 v50, v234, v235
	v_cvt_pk_bf16_f32 v51, v236, v237
	s_waitcnt lgkmcnt(2)
	s_nop 0
	v_mfma_f32_32x32x16_bf16 v[16:31], v[52:55], v[48:51], v[16:31]
	s_waitcnt lgkmcnt(0)
	v_mfma_f32_32x32x16_bf16 v[0:15], v[56:59], v[48:51], v[0:15]
	ds_read_b64_tr_b16 v[52:53], v76 offset:2304
	ds_read_b64_tr_b16 v[54:55], v76 offset:3456
	ds_read_b64_tr_b16 v[56:57], v76 offset:2368
	ds_read_b64_tr_b16 v[58:59], v76 offset:3520
	v_cvt_pk_bf16_f32 v48, v186, v187
	v_cvt_pk_bf16_f32 v49, v188, v189
	v_cvt_pk_bf16_f32 v50, v190, v191
	v_cvt_pk_bf16_f32 v51, v192, v194
	s_waitcnt lgkmcnt(2)
	s_nop 0
	v_mfma_f32_32x32x16_bf16 v[16:31], v[52:55], v[48:51], v[16:31]
	s_waitcnt lgkmcnt(0)
	v_mfma_f32_32x32x16_bf16 v[0:15], v[56:59], v[48:51], v[0:15]
	s_waitcnt vmcnt(3)
	ds_write_b128 v175, v[32:35]
	s_waitcnt vmcnt(2)
	ds_write_b128 v64, v[36:39]
	s_waitcnt vmcnt(1)
	ds_write_b128 v66, v[40:43]
	s_waitcnt vmcnt(0)
	ds_write_b128 v68, v[44:47]
	ds_read_b64_tr_b16 v[36:37], v76
	ds_read_b64_tr_b16 v[38:39], v76 offset:1152
	ds_read_b64_tr_b16 v[40:41], v76 offset:64
	ds_read_b64_tr_b16 v[42:43], v76 offset:1216
	v_cvt_pk_bf16_f32 v32, v178, v179
	v_cvt_pk_bf16_f32 v33, v180, v181
	v_cvt_pk_bf16_f32 v34, v182, v183
	v_cvt_pk_bf16_f32 v35, v184, v185
	s_waitcnt lgkmcnt(2)
	s_nop 0
	v_mfma_f32_32x32x16_bf16 v[16:31], v[36:39], v[32:35], v[16:31]
	s_waitcnt lgkmcnt(0)
	v_mfma_f32_32x32x16_bf16 v[0:15], v[40:43], v[32:35], v[0:15]
	ds_read_b64_tr_b16 v[36:37], v76 offset:2304
	ds_read_b64_tr_b16 v[38:39], v76 offset:3456
	ds_read_b64_tr_b16 v[40:41], v76 offset:2368
	ds_read_b64_tr_b16 v[42:43], v76 offset:3520
	v_cvt_pk_bf16_f32 v32, v73, v74
	v_cvt_pk_bf16_f32 v33, v75, v77
	v_cvt_pk_bf16_f32 v35, v176, v177
	v_cvt_pk_bf16_f32 v34, v78, v79
	s_waitcnt lgkmcnt(2)
	s_nop 0
	v_mfma_f32_32x32x16_bf16 v[16:31], v[36:39], v[32:35], v[16:31]
	v_lshl_add_u64 v[44:45], s[18:19], 0, v[146:147]
	global_store_dwordx4 v[44:45], v[84:87], off nt
	v_lshl_add_u64 v[44:45], s[18:19], 0, v[148:149]
	global_store_dwordx4 v[44:45], v[80:83], off nt
	v_lshl_add_u64 v[44:45], s[18:19], 0, v[150:151]
	global_store_dwordx4 v[44:45], v[92:95], off nt
	v_lshl_add_u64 v[44:45], s[18:19], 0, v[152:153]
	s_waitcnt lgkmcnt(0)
	v_mfma_f32_32x32x16_bf16 v[0:15], v[40:43], v[32:35], v[0:15]
	v_add_f32_e32 v33, v71, v72
	v_div_scale_f32 v32, s[0:1], v33, v33, 1.0
	v_rcp_f32_e32 v34, v32
	global_store_dwordx4 v[44:45], v[88:91], off nt
	v_fma_f32 v35, -v32, v34, 1.0
	v_fmac_f32_e32 v34, v35, v34
	v_div_scale_f32 v35, vcc, 1.0, v33, 1.0
	v_mul_f32_e32 v36, v35, v34
	v_fma_f32 v37, -v32, v36, v35
	v_fmac_f32_e32 v36, v37, v34
	v_fma_f32 v32, -v32, v36, v35
	v_log_f32_e32 v35, v33
	v_div_fmas_f32 v32, v32, v34, v36
	v_div_fixup_f32 v32, v32, v33, 1.0
	v_subrev_u32_e32 v33, s84, v174
	v_cndmask_b32_e64 v34, 0, 1, s[54:55]
	v_fmac_f32_e32 v35, 0x3e38aa3b, v70
	v_cmp_ne_u32_e64 s[38:39], 1, v34
	s_andn2_b64 vcc, exec, s[54:55]
	v_lshl_add_u32 v36, v33, 2, 0
	s_cbranch_vccnz .LBB0_358
	v_add_u32_e32 v34, 0x12000, v36
	ds_read_b32 v34, v34
	v_max_f32_e32 v37, v35, v35
	s_waitcnt lgkmcnt(0)
	v_max_f32_e32 v38, v34, v34
	v_max_f32_e32 v37, v38, v37
	v_sub_f32_e32 v38, v34, v37
	v_sub_f32_e32 v39, v35, v37
	v_exp_f32_e32 v38, v38
	v_exp_f32_e32 v39, v39
	s_nop 0
	v_add_f32_e32 v38, v38, v39
	v_log_f32_e32 v38, v38
	s_nop 0
	v_add_f32_e32 v37, v37, v38
	v_sub_f32_e32 v35, v35, v37
	v_exp_f32_e32 v35, v35
	v_sub_f32_e32 v34, v34, v37
	v_exp_f32_e32 v34, v34
	v_mul_f32_e32 v32, v32, v35
	v_mov_b32_e32 v35, v37
	s_branch .LBB0_359
